# attention prompt-unit loop: one static s_setprio 1 for waves 4-7 (second wave of each SIMD), reset after the loop
# speedup vs baseline: 1.0005x; 1.0005x over previous
.LBB0_543:
	s_andn2_b64 vcc, exec, s[0:1]
	s_cbranch_vccnz .LBB0_589
	s_cmp_eq_u32 s50, 6
	s_cbranch_scc0 .LBB0_589
	s_waitcnt vmcnt(0)
	v_mov_b32_e32 v76, v204
	s_mov_b32 s51, s2
	v_readfirstlane_b32 s0, v76
	s_ashr_i32 s68, s0, 6
	v_readlane_b32 s0, v252, 20
	v_readlane_b32 s1, v252, 21
	s_andn2_b64 vcc, exec, s[0:1]
	s_movk_i32 s0, 0x500
	v_cmp_gt_i32_e64 s[0:1], s0, v76
	v_and_b32_e32 v103, 15, v76
	v_bfe_u32 v136, v76, 4, 2
	v_writelane_b32 v255, s0, 3
	v_lshlrev_b32_e32 v78, 2, v136
	v_or_b32_e32 v0, 0x80, v103
	v_writelane_b32 v255, s1, 4
	s_movk_i32 s0, 0x90
	v_lshlrev_b32_e32 v80, 4, v136
	v_mul_u32_u24_e32 v77, 0x150, v103
	v_mad_u32_u24 v79, v103, s0, 0
	v_sub_u32_e32 v137, v0, v78
	s_cbranch_vccnz .LBB0_566
	s_waitcnt lgkmcnt(0)
	v_min_i32_e32 v3, 0x4ff, v76
	v_ashrrev_i32_e32 v138, 3, v3
	v_readlane_b32 s2, v252, 22
	v_readlane_b32 s0, v252, 29
	s_mov_b32 s8, s0
	v_add_u32_e32 v0, s2, v138
	v_max_i32_e32 v0, 0, v0
	v_add_u32_e32 v0, s8, v0
	v_ashrrev_i32_e32 v1, 31, v0
	v_readlane_b32 s6, v252, 27
	v_lshlrev_b64 v[0:1], 10, v[0:1]
	v_readlane_b32 s7, v252, 28
	s_mov_b32 s3, 0x66666667
	v_mov_b32_e32 v7, v2
	v_lshl_add_u64 v[4:5], s[6:7], 0, v[0:1]
	v_lshlrev_b32_e32 v0, 3, v3
	v_and_b32_e32 v0, 56, v0
	v_lshlrev_b32_e32 v6, 1, v0
	v_mul_hi_i32 v1, v3, s3
	v_lshl_add_u64 v[4:5], v[4:5], 0, v[6:7]
	v_lshrrev_b32_e32 v6, 31, v1
	v_ashrrev_i32_e32 v1, 3, v1
	v_readlane_b32 s1, v252, 30
	v_add_u32_e32 v139, v1, v6
	s_movk_i32 s5, 0xffec
	v_mul_lo_u32 v1, v139, s5
	v_readlane_b32 s0, v252, 23
	v_add_lshl_u32 v140, v1, v3, 3
	v_readlane_b32 s1, v252, 24
	v_add_u32_e32 v1, s2, v140
	s_mov_b32 s4, s0
	v_readlane_b32 s0, v252, 33
	v_max_i32_e32 v1, 0, v1
	v_readlane_b32 s1, v252, 34
	v_add_u32_e32 v3, s4, v139
	v_lshlrev_b32_e32 v8, 1, v1
	v_mov_b64_e32 v[20:21], s[0:1]
	v_min_i32_e32 v1, 0x2ff, v76
	v_mad_i64_i32 v[6:7], s[0:1], v3, s93, v[20:21]
	v_add_u32_e32 v3, 0x200, v1
	v_ashrrev_i32_e32 v141, 3, v3
	v_add_u32_e32 v12, s2, v141
	v_max_i32_e32 v12, 0, v12
	v_add_u32_e32 v12, s8, v12
	v_ashrrev_i32_e32 v13, 31, v12
	v_lshlrev_b32_e32 v1, 3, v1
	v_lshlrev_b64 v[12:13], 10, v[12:13]
	v_and_b32_e32 v28, 56, v1
	v_lshl_add_u64 v[12:13], s[6:7], 0, v[12:13]
	v_lshlrev_b32_e32 v14, 1, v28
	v_mov_b32_e32 v15, v2
	v_mul_hi_i32 v1, v3, s3
	v_lshl_add_u64 v[12:13], v[12:13], 0, v[14:15]
	v_lshrrev_b32_e32 v14, 31, v1
	v_ashrrev_i32_e32 v1, 3, v1
	v_add_u32_e32 v142, v1, v14
	v_mul_lo_u32 v1, v142, s5
	v_add_lshl_u32 v143, v1, v3, 3
	v_add_u32_e32 v1, s2, v143
	v_max_i32_e32 v1, 0, v1
	v_add_u32_e32 v3, s4, v142
	v_lshlrev_b32_e32 v16, 1, v1
	v_min_i32_e32 v1, 0xff, v76
	v_mad_i64_i32 v[14:15], s[0:1], v3, s93, v[20:21]
	v_add_u32_e32 v3, 0x400, v1
	v_ashrrev_i32_e32 v144, 3, v3
	v_add_u32_e32 v22, s2, v144
	v_max_i32_e32 v22, 0, v22
	v_add_u32_e32 v22, s8, v22
	v_ashrrev_i32_e32 v23, 31, v22
	v_lshlrev_b32_e32 v1, 3, v1
	v_lshlrev_b64 v[22:23], 10, v[22:23]
	v_and_b32_e32 v30, 56, v1
	v_lshl_add_u64 v[22:23], s[6:7], 0, v[22:23]
	v_lshlrev_b32_e32 v24, 1, v30
	v_mov_b32_e32 v25, v2
	v_mul_hi_i32 v1, v3, s3
	v_lshl_add_u64 v[22:23], v[22:23], 0, v[24:25]
	v_lshrrev_b32_e32 v24, 31, v1
	v_ashrrev_i32_e32 v1, 3, v1
	v_add_u32_e32 v145, v1, v24
	v_mul_lo_u32 v1, v145, s5
	v_add_lshl_u32 v146, v1, v3, 3
	v_add_u32_e32 v1, s2, v146
	v_max_i32_e32 v1, 0, v1
	v_add_u32_e32 v3, s4, v145
	v_mov_b32_e32 v9, v2
	v_mov_b32_e32 v17, v2
	v_mad_i64_i32 v[20:21], s[0:1], v3, s93, v[20:21]
	v_lshlrev_b32_e32 v24, 1, v1
	v_lshl_add_u64 v[8:9], v[6:7], 0, v[8:9]
	v_lshl_add_u64 v[16:17], v[14:15], 0, v[16:17]
	v_lshl_add_u64 v[24:25], v[20:21], 0, v[24:25]
	global_load_dwordx4 v[4:7], v[4:5], off
	s_nop 0
	global_load_dwordx4 v[8:11], v[8:9], off
	s_nop 0
	global_load_dwordx4 v[12:15], v[12:13], off
	s_nop 0
	global_load_dwordx4 v[16:19], v[16:17], off
	s_nop 0
	global_load_dwordx4 v[20:23], v[22:23], off
	s_nop 0
	global_load_dwordx4 v[24:27], v[24:25], off
	v_mul_hi_i32 v29, v76, s3
	v_readlane_b32 s0, v251, 22
	v_lshrrev_b32_e32 v31, 31, v29
	v_ashrrev_i32_e32 v29, 3, v29
	v_lshlrev_b32_e32 v32, 3, v136
	v_mov_b32_e32 v33, v2
	v_readlane_b32 s1, v251, 23
	v_add_u32_e32 v29, v29, v31
	s_movk_i32 s4, 0x150
	v_lshl_add_u64 v[84:85], s[0:1], 0, v[32:33]
	v_mad_u64_u32 v[34:35], s[0:1], v29, s5, v[76:77]
	v_lshlrev_b32_e32 v147, 3, v34
	v_lshlrev_b32_e32 v31, 4, v34
	v_add_u32_e32 v34, 0x200, v76
	s_movk_i32 s0, 0x300
	v_mul_hi_i32 v35, v34, s3
	v_cmp_gt_i32_e64 s[0:1], s0, v76
	v_lshrrev_b32_e32 v37, 31, v35
	v_ashrrev_i32_e32 v35, 3, v35
	v_writelane_b32 v255, s0, 5
	v_add_u32_e32 v37, v35, v37
	v_ashrrev_i32_e32 v148, 3, v34
	v_writelane_b32 v255, s1, 6
	v_mad_u64_u32 v[34:35], s[0:1], v37, s5, v[34:35]
	v_lshlrev_b32_e32 v149, 3, v34
	v_mul_lo_u32 v35, v37, s4
	v_lshlrev_b32_e32 v38, 4, v34
	v_add_u32_e32 v34, 0x400, v76
	v_add_u32_e32 v37, 0, v35
	s_movk_i32 s0, 0x100
	v_mul_hi_i32 v35, v34, s3
	v_cmp_gt_i32_e64 s[0:1], s0, v76
	v_lshrrev_b32_e32 v40, 31, v35
	v_ashrrev_i32_e32 v35, 3, v35
	v_writelane_b32 v255, s0, 7
	v_add_u32_e32 v40, v35, v40
	v_ashrrev_i32_e32 v150, 3, v34
	v_writelane_b32 v255, s1, 8
	v_mad_u64_u32 v[34:35], s[0:1], v40, s5, v[34:35]
	v_readlane_b32 s0, v255, 1
	v_readlane_b32 s1, v255, 2
	s_lshl_b32 s0, s0, 6
	v_writelane_b32 v255, s0, 9
	v_readlane_b32 s0, v253, 53
	v_readlane_b32 s1, v253, 54
	v_mul_lo_u32 v29, v29, s4
	v_mul_lo_u32 v35, v40, s4
	v_lshl_add_u64 v[86:87], s[0:1], 0, v[32:33]
	s_movk_i32 s1, 0x80
	v_cmp_gt_u32_e64 s[4:5], s1, v137
	s_movk_i32 s0, 0x81
	v_add_u32_e32 v33, -3, v137
	v_writelane_b32 v255, s4, 10
	v_add_u32_e32 v40, 0, v32
	v_add_u32_e32 v32, -2, v137
	v_writelane_b32 v255, s5, 11
	v_cmp_gt_u32_e64 s[4:5], s0, v137
	s_movk_i32 s0, 0x7f
	v_or_b32_e32 v42, 0x90, v103
	v_writelane_b32 v255, s4, 12
	v_mov_b32_e32 v81, v2
	v_sub_u32_e32 v42, v42, v78
	v_writelane_b32 v255, s5, 13
	v_cmp_gt_u32_e64 s[4:5], s1, v33
	v_add_u32_e32 v33, 0xffffff7e, v137
	v_lshl_add_u64 v[82:83], s[64:65], 0, v[80:81]
	v_writelane_b32 v255, s4, 14
	v_ashrrev_i32_e32 v81, 3, v76
	s_movk_i32 s2, 0x90
	v_writelane_b32 v255, s5, 15
	v_cmp_gt_u32_e64 s[4:5], s1, v32
	v_add_u32_e32 v32, 0xffffff7f, v137
	v_or_b32_e32 v153, 16, v103
	v_writelane_b32 v255, s4, 16
	v_subrev_u32_e32 v44, 17, v42
	v_mul_lo_u32 v3, v81, s2
	v_writelane_b32 v255, s5, 17
	v_cmp_lt_u32_e64 s[4:5], s0, v137
	v_mul_lo_u32 v36, v148, s2
	v_mul_lo_u32 v39, v150, s2
	v_writelane_b32 v255, s4, 18
	v_mad_u32_u24 v154, v153, s2, 0
	v_cmp_gt_u32_e64 s[2:3], s1, v44
	v_writelane_b32 v255, s5, 19
	v_cmp_gt_u32_e64 s[4:5], s1, v33
	v_add_u32_e32 v43, -16, v42
	v_subrev_u32_e32 v44, 19, v42
	v_writelane_b32 v255, s4, 20
	v_lshlrev_b32_e32 v1, 4, v76
	v_cvt_f32_ubyte0_e32 v155, v42
	v_writelane_b32 v255, s5, 21
	v_cmp_gt_u32_e64 s[4:5], s1, v32
	v_add_u32_e32 v32, 0xffffff7d, v137
	v_and_b32_e32 v1, 0x70, v1
	v_writelane_b32 v255, s4, 22
	v_add_u32_e32 v1, 0, v1
	v_add_u32_e32 v29, 0, v29
	v_writelane_b32 v255, s5, 23
	v_cmp_gt_u32_e64 s[4:5], s1, v32
	v_lshlrev_b32_e32 v151, 3, v34
	v_add_u32_e32 v35, 0, v35
	v_writelane_b32 v255, s4, 24
	v_lshlrev_b32_e32 v34, 4, v34
	v_add_u32_e32 v32, 0x900, v154
	v_writelane_b32 v255, s5, 25
	v_writelane_b32 v255, s2, 26
	v_add_u32_e32 v33, 0x1200, v154
	v_add_u32_e32 v41, 0x3f00, v154
	v_writelane_b32 v255, s3, 27
	v_cmp_gt_u32_e64 s[2:3], s1, v43
	v_subrev_u32_e32 v43, 18, v42
	v_cvt_f32_ubyte0_e32 v152, v137
	v_writelane_b32 v255, s2, 28
	v_add_u32_e32 v156, v1, v3
	v_add_u32_e32 v157, v29, v31
	v_writelane_b32 v255, s3, 29
	v_cmp_gt_u32_e64 s[2:3], s1, v44
	v_add_u32_e32 v44, 0xffffff6f, v42
	v_add_u32_e32 v158, v1, v36
	v_writelane_b32 v255, s2, 30
	v_add_u32_e32 v159, v37, v38
	v_add_u32_e32 v161, v1, v39
	v_writelane_b32 v255, s3, 31
	v_cmp_gt_u32_e64 s[2:3], s1, v43
	v_add_u32_e32 v43, 0xffffff70, v42
	v_add_u32_e32 v166, v35, v34
	v_writelane_b32 v255, s2, 32
	v_lshlrev_b32_e32 v88, 1, v0
	v_lshlrev_b32_e32 v90, 1, v28
	v_writelane_b32 v255, s3, 33
	v_cmp_gt_u32_e64 s[2:3], s1, v44
	v_lshlrev_b32_e32 v92, 1, v30
	v_add_u32_e32 v167, v32, v80
	v_writelane_b32 v255, s2, 34
	v_add_u32_e32 v168, v33, v80
	v_add_u32_e32 v169, v41, v80
	v_writelane_b32 v255, s3, 35
	v_cmp_gt_u32_e64 s[2:3], s1, v43
	v_add_u32_e32 v43, 0xffffff6e, v42
	v_add_u32_e32 v42, 0xffffff6d, v42
	v_writelane_b32 v255, s2, 36
	v_add_u32_e32 v170, v79, v80
	v_add_u32_e32 v171, v40, v77
	v_writelane_b32 v255, s3, 37
	v_cmp_gt_u32_e64 s[2:3], s1, v43
	v_cmp_gt_u32_e64 s[0:1], s1, v42
	s_mov_b32 s6, s51
	v_writelane_b32 v255, s2, 38
	s_nop 1
	v_writelane_b32 v255, s3, 39
	v_writelane_b32 v255, s0, 40
	s_nop 1
	v_writelane_b32 v255, s1, 41
	s_cmp_lt_u32 s68, 4
	s_cbranch_scc1 .Lattn_prio_skip
	s_setprio 1
.Lattn_prio_skip:
	s_branch .LBB0_548
.LBB0_547:
	s_or_b64 exec, exec, s[0:1]
	s_andn2_b64 vcc, exec, s[2:3]
	s_mov_b32 s6, s46
	s_cbranch_vccz .LBB0_566

.LBB0_566:
	s_setprio 0
	v_readlane_b32 s0, v252, 36
	v_readlane_b32 s1, v252, 37
	v_readlane_b32 s34, v254, 48
	s_andn2_b64 vcc, exec, s[0:1]
	s_mov_b32 s2, s51
	v_readlane_b32 s35, v254, 49
	v_readlane_b32 s70, v254, 54
	v_readlane_b32 s60, v254, 50
	v_readlane_b32 s36, v254, 51
	v_readlane_b32 s44, v254, 52
	v_readlane_b32 s4, v254, 57
	v_readlane_b32 s45, v254, 53
	v_readlane_b32 s5, v254, 58
	s_cbranch_vccnz .LBB0_589
	v_and_b32_e32 v1, 64, v208
	v_xor_b32_e32 v0, 16, v208
	v_add_u32_e32 v1, 64, v1
	v_cmp_lt_i32_e32 vcc, v0, v1
	s_movk_i32 s0, 0x500
	v_cmp_gt_i32_e64 s[38:39], s0, v76
	v_cndmask_b32_e32 v0, v208, v0, vcc
	v_lshlrev_b32_e32 v25, 2, v0
	v_xor_b32_e32 v0, 32, v208
	v_readlane_b32 s0, v255, 1
	v_cmp_lt_i32_e32 vcc, v0, v1
	s_lshl_b32 s16, s0, 6
	s_movk_i32 s0, 0x81
	v_cndmask_b32_e32 v0, v208, v0, vcc
	v_lshlrev_b32_e32 v34, 2, v0
	s_movk_i32 s3, 0x80
	v_subrev_co_u32_e64 v0, s[42:43], s0, v137
	v_add_u32_e32 v1, -2, v137
	v_cmp_gt_u32_e64 s[4:5], s3, v0
	v_add_u32_e32 v0, 0xffffff7e, v137
	v_readlane_b32 s1, v255, 2
	v_cmp_gt_u32_e64 s[44:45], s3, v1
	v_add_u32_e32 v1, -3, v137
	v_cmp_gt_u32_e64 s[50:51], s3, v0
	v_add_u32_e32 v0, 0xffffff7d, v137
	v_and_b32_e32 v4, 7, v76
	v_readlane_b32 s6, v252, 25
	v_cmp_gt_u32_e64 s[0:1], s3, v1
	v_cmp_gt_u32_e64 s[52:53], s3, v0
	v_lshlrev_b32_e32 v0, 4, v4
	v_mov_b32_e32 v1, v2
	v_readlane_b32 s7, v252, 26
	v_readlane_b32 s76, v251, 55
	v_and_b32_e32 v35, 63, v76
	v_lshl_add_u64 v[22:23], s[6:7], 0, v[0:1]
	v_add_u32_e32 v24, 0, v0
	v_lshlrev_b32_e32 v0, 5, v4
	v_readlane_b32 s82, v251, 61
	v_readlane_b32 s83, v251, 62
	v_mov_b32_e32 v81, v2
	s_waitcnt lgkmcnt(0)
	v_lshl_add_u32 v3, v136, 3, 0
	v_cmp_gt_u32_e64 s[40:41], s3, v137
	s_movk_i32 s3, 0x150
	v_readlane_b32 s84, v251, 63
	v_readlane_b32 s85, v252, 0
	v_lshl_add_u64 v[26:27], s[82:83], 0, v[0:1]
	v_lshlrev_b32_e32 v0, 2, v35
	v_lshl_add_u64 v[20:21], s[64:65], 0, v[80:81]
	v_cvt_f32_ubyte0_e32 v161, v137
	v_cmp_gt_u32_e64 s[54:55], 8, v103
	v_mad_u32_u24 v36, v35, s3, 0
	v_or_b32_e32 v37, 0x2040, v103
	v_lshl_add_u64 v[28:29], s[84:85], 0, v[0:1]
	v_add_u32_e32 v38, v79, v80
	v_add_u32_e32 v39, v3, v77
	v_readlane_b32 s17, v252, 35
	v_readlane_b32 s77, v251, 56
	v_readlane_b32 s78, v251, 57
	v_readlane_b32 s79, v251, 58
	v_readlane_b32 s80, v251, 59
	v_readlane_b32 s81, v251, 60
	v_readlane_b32 s86, v252, 1
	v_readlane_b32 s87, v252, 2
	v_readlane_b32 s88, v252, 3
	v_readlane_b32 s89, v252, 4
	v_readlane_b32 s90, v252, 5
	v_readlane_b32 s91, v252, 6
	s_branch .LBB0_569
